# knorm: 4 bf16 (dwordx2) per lane, KS and KW of a row in one instruction; even/odd chains only after the in-lane steps, DPP for lane xor 1/2/8 and one bpermute step; quarter of the original knorm VMEM
# speedup vs baseline: 1.0149x; 1.0023x over previous
; __device__ __forceinline__ float bf2f(unsigned short u) { return __uint_as_float((unsigned)u << 16); }
; __device__ __forceinline__ unsigned f2bf(float f) { unsigned u = __float_as_uint(f); return (u + 0x7fffu + ((u >> 16) & 1u)) >> 16; }
; __device__ __forceinline__ void knorm_item(const KArgs& a, int l, int item, int wave, int lane) {
;     const bf16_t* Z = (const bf16_t*)(a.ws + WS_Z);
;     const float kg = a.in[I_KN][l * 64 + lane];
;     for (int r0 = 0; r0 < 128; r0 += 16) {
;         float v[16];
; #pragma unroll
;         for (int i = 0; i < 16; ++i) { const int task = item * 1024 + wave * 128 + r0 + i, row = task >> 2, which = (task >> 1) & 1, g = task & 1;
;             v[i] = bf2f(Z[(size_t)row * ZW + (which ? ZC_KW : ZC_KS) + g * 64 + lane]); }
; #pragma unroll
;         for (int i = 0; i < 16; ++i) { const int task = item * 1024 + wave * 128 + r0 + i, row = task >> 2, which = (task >> 1) & 1, g = task & 1;
;             const float rstd = rsqrtf(wave_sum(v[i] * v[i]) * (1.f / 64.f) + EPS);
;             bf16_t* dst = (bf16_t*)(a.ws + (which ? WS_KWN : WS_KSN));
;             dst[(size_t)row * 128 + g * 64 + lane] = (bf16_t)f2bf(v[i] * rstd * kg); }
; __device__ __forceinline__ void phase_mix1(const KArgs& a, int l, LAS unsigned char* lds, int wave, int lane, int ci) {
;     ...
;         __syncthreads();
;         if (threadIdx.x == 0) *slot = (int)atomicAdd(ctr, 1u);
;         __syncthreads();
;         int r = *slot;
;         if (r >= N_R0 + N_CMP + N_CONV + N_KN) break;
;         if (r < N_R0) { ret0_item(a, l, r, lds, wave, lane); continue; } r -= N_R0;
;         if (r < N_CMP) { cmp_mfma_item(a, l, r, lds, wave, lane); continue; } r -= N_CMP;
;         if (r < N_CONV) { conv_item(a, l, r); continue; } r -= N_CONV;
;         knorm_item(a, l, r, wave, lane);
.LBB0_232:
	s_or_b64 exec, exec, s[0:1]
	s_waitcnt lgkmcnt(0)
	s_barrier
	ds_read_b32 v0, v120
	s_movk_i32 s0, 0x2ff
	s_waitcnt lgkmcnt(0)
	v_cmp_lt_i32_e32 vcc, s0, v0
	v_readfirstlane_b32 s33, v0
	s_mov_b64 s[0:1], -1
	s_cbranch_vccnz .LBB0_227
	s_cmpk_gt_i32 s33, 0x7f
	s_cbranch_scc0 .LBB0_262
	s_cmpk_gt_u32 s33, 0xff
	s_cbranch_scc0 .LBB0_243
	s_cmpk_gt_u32 s33, 0x1ff
	s_cbranch_scc0 .LBB0_239
	global_load_dword v8, v[66:67], off
	v_cmp_lt_i32_e32 vcc, v124, v123
	s_lshl_b32 s0, s33, 10
	s_add_i32 s24, s34, s0
	v_cndmask_b32_e32 v0, v122, v124, vcc
	v_cmp_lt_i32_e32 vcc, v125, v123
	v_lshlrev_b32_e32 v9, 2, v0
	s_mov_b32 s57, -16
	v_cndmask_b32_e32 v0, v122, v125, vcc
	v_cmp_lt_i32_e32 vcc, v126, v123
	v_lshlrev_b32_e32 v10, 2, v0
	s_nop 0
	v_cndmask_b32_e32 v0, v122, v126, vcc
	v_cmp_lt_i32_e32 vcc, v127, v123
	v_lshlrev_b32_e32 v11, 2, v0
	s_nop 0
	v_cndmask_b32_e32 v0, v122, v127, vcc
	v_cmp_lt_i32_e32 vcc, v128, v123
	v_lshlrev_b32_e32 v12, 2, v0
	s_nop 0
	v_cndmask_b32_e32 v0, v122, v128, vcc
	v_cmp_lt_i32_e32 vcc, v129, v123
	v_lshlrev_b32_e32 v13, 2, v0
	s_nop 0
	v_cndmask_b32_e32 v0, v122, v129, vcc
	v_lshlrev_b32_e32 v14, 2, v0
	v_mbcnt_lo_u32_b32 v186, -1, 0
	v_mbcnt_hi_u32_b32 v186, -1, v186
	v_and_b32_e32 v188, 15, v186
	v_lshlrev_b32_e32 v188, 4, v188
	v_lshlrev_b32_e32 v187, 2, v186
	v_sub_u32_e32 v188, v188, v187
	v_ashrrev_i32_e32 v189, 31, v188
	v_lshl_add_u64 v[188:189], v[66:67], 0, v[188:189]
	global_load_dwordx4 v[184:187], v[188:189], off
	v_mbcnt_lo_u32_b32 v202, -1, 0
	v_mbcnt_hi_u32_b32 v202, -1, v202
	v_and_b32_e32 v188, 31, v202
	v_lshlrev_b32_e32 v188, 3, v188
	v_lshlrev_b32_e32 v189, 1, v202
	v_sub_u32_e32 v188, v188, v189
	v_ashrrev_i32_e32 v189, 31, v188
	v_lshl_add_u64 v[190:191], v[68:69], 0, v[188:189]
	v_lshl_add_u64 v[192:193], v[70:71], 0, v[188:189]
	v_cmp_lt_u32_e32 vcc, 31, v202
	v_lshrrev_b32_e32 v203, 5, v202
	v_lshlrev_b32_e32 v203, 9, v203
	v_cndmask_b32_e32 v190, v190, v192, vcc
	v_cndmask_b32_e32 v191, v191, v193, vcc
	v_add_u32_e32 v188, v188, v203
	v_mov_b32_e32 v189, 0
	v_lshl_add_u64 v[192:193], v[64:65], 0, v[188:189]
	v_mov_b32_e32 v188, s47
	v_lshl_add_u64 v[192:193], v[192:193], 0, v[188:189]
	v_mov_b32_e32 v194, 0x7060302
	v_mov_b32_e32 v195, s20
	s_add_i32 s0, s24, s57
	s_add_i32 s0, s0, 0xfff80010
	s_ashr_i32 s4, s0, 2
	s_ashr_i32 s5, s4, 31
	s_mul_i32 s0, s4, 0x1a00
	s_mul_hi_i32 s1, s4, 0x1a00
	s_add_u32 s0, s92, s0
	s_addc_u32 s1, s93, s1
	v_lshl_add_u64 v[0:1], s[0:1], 0, v[192:193]
	global_load_dwordx2 v[16:17], v[0:1], off offset:1024
	s_add_u32 s0, s0, 0x1a00
	s_addc_u32 s1, s1, 0
	v_lshl_add_u64 v[2:3], s[0:1], 0, v[192:193]
	global_load_dwordx2 v[18:19], v[2:3], off offset:1024
	s_add_u32 s0, s0, 0x1a00
	s_addc_u32 s1, s1, 0
	v_lshl_add_u64 v[0:1], s[0:1], 0, v[192:193]
	global_load_dwordx2 v[20:21], v[0:1], off offset:1024
	s_add_u32 s0, s0, 0x1a00
	s_addc_u32 s1, s1, 0
	v_lshl_add_u64 v[2:3], s[0:1], 0, v[192:193]
	global_load_dwordx2 v[22:23], v[2:3], off offset:1024
.LBB0_237:
	s_add_i32 s0, s24, s57
	s_add_i32 s0, s0, 0xfff80020
	s_ashr_i32 s4, s0, 2
	s_ashr_i32 s5, s4, 31
	s_mul_i32 s0, s4, 0x1a00
	s_mul_hi_i32 s1, s4, 0x1a00
	s_add_u32 s0, s92, s0
	s_addc_u32 s1, s93, s1
	v_lshl_add_u64 v[0:1], s[0:1], 0, v[192:193]
	global_load_dwordx2 v[24:25], v[0:1], off offset:1024
	s_add_u32 s0, s0, 0x1a00
	s_addc_u32 s1, s1, 0
	v_lshl_add_u64 v[2:3], s[0:1], 0, v[192:193]
	global_load_dwordx2 v[26:27], v[2:3], off offset:1024
	s_add_u32 s0, s0, 0x1a00
	s_addc_u32 s1, s1, 0
	v_lshl_add_u64 v[0:1], s[0:1], 0, v[192:193]
	global_load_dwordx2 v[196:197], v[0:1], off offset:1024
	s_add_u32 s0, s0, 0x1a00
	s_addc_u32 s1, s1, 0
	v_lshl_add_u64 v[2:3], s[0:1], 0, v[192:193]
	global_load_dwordx2 v[198:199], v[2:3], off offset:1024
	s_add_i32 s0, s24, s57
	s_add_i32 s0, s0, 0xfff80010
	s_ashr_i32 s4, s0, 2
	s_ashr_i32 s5, s4, 31
	s_lshl_b64 s[30:31], s[4:5], 8
	v_lshl_add_u64 v[200:201], v[190:191], 0, s[30:31]
	s_waitcnt vmcnt(6)
	v_lshlrev_b32_e32 v220, 16, v16
	v_and_b32_e32 v221, 0xffff0000, v16
	v_lshlrev_b32_e32 v222, 16, v17
	v_and_b32_e32 v223, 0xffff0000, v17
	v_lshlrev_b32_e32 v236, 16, v18
	v_and_b32_e32 v237, 0xffff0000, v18
	v_lshlrev_b32_e32 v238, 16, v19
	v_and_b32_e32 v239, 0xffff0000, v19
	v_mul_f32_e32 v224, v220, v220
	v_mul_f32_e32 v225, v221, v221
	v_mul_f32_e32 v226, v222, v222
	v_mul_f32_e32 v227, v223, v223
	v_mul_f32_e32 v240, v236, v236
	v_mul_f32_e32 v241, v237, v237
	v_mul_f32_e32 v242, v238, v238
	v_mul_f32_e32 v243, v239, v239
	v_fma_f32 v228, v220, v220, v225
	v_fma_f32 v229, v221, v221, v224
	v_fma_f32 v230, v222, v222, v227
	v_fma_f32 v231, v223, v223, v226
	v_fma_f32 v244, v236, v236, v241
	v_fma_f32 v245, v237, v237, v240
	v_fma_f32 v246, v238, v238, v243
	v_fma_f32 v247, v239, v239, v242
	v_add_f32_e32 v228, v228, v230
	v_add_f32_e32 v229, v229, v231
	v_add_f32_e32 v244, v244, v246
	v_add_f32_e32 v245, v245, v247
	v_add_f32_dpp v228, v228, v228 quad_perm:[1,0,3,2] row_mask:0xf bank_mask:0xf
	v_add_f32_dpp v229, v229, v229 quad_perm:[1,0,3,2] row_mask:0xf bank_mask:0xf
	v_add_f32_dpp v244, v244, v244 quad_perm:[1,0,3,2] row_mask:0xf bank_mask:0xf
	v_add_f32_dpp v245, v245, v245 quad_perm:[1,0,3,2] row_mask:0xf bank_mask:0xf
	v_add_f32_dpp v228, v228, v228 quad_perm:[2,3,0,1] row_mask:0xf bank_mask:0xf
	v_add_f32_dpp v229, v229, v229 quad_perm:[2,3,0,1] row_mask:0xf bank_mask:0xf
	v_add_f32_dpp v244, v244, v244 quad_perm:[2,3,0,1] row_mask:0xf bank_mask:0xf
	v_add_f32_dpp v245, v245, v245 quad_perm:[2,3,0,1] row_mask:0xf bank_mask:0xf
	ds_bpermute_b32 v230, v11, v228
	ds_bpermute_b32 v231, v11, v229
	ds_bpermute_b32 v246, v11, v244
	ds_bpermute_b32 v247, v11, v245
	s_waitcnt lgkmcnt(0)
; __device__ __forceinline__ float bf2f(unsigned short u) { return __uint_as_float((unsigned)u << 16); }
; __device__ __forceinline__ unsigned f2bf(float f) { unsigned u = __float_as_uint(f); return (u + 0x7fffu + ((u >> 16) & 1u)) >> 16; }
; __device__ __forceinline__ void knorm_item(const KArgs& a, int l, int item, int wave, int lane) {
;     ...
;     for (int r0 = 0; r0 < 128; r0 += 16) {
;         float v[16];
; #pragma unroll
;         for (int i = 0; i < 16; ++i) { const int task = item * 1024 + wave * 128 + r0 + i, row = task >> 2, which = (task >> 1) & 1, g = task & 1;
;             v[i] = bf2f(Z[(size_t)row * ZW + (which ? ZC_KW : ZC_KS) + g * 64 + lane]); }
; #pragma unroll
;         for (int i = 0; i < 16; ++i) { const int task = item * 1024 + wave * 128 + r0 + i, row = task >> 2, which = (task >> 1) & 1, g = task & 1;
;             const float rstd = rsqrtf(wave_sum(v[i] * v[i]) * (1.f / 64.f) + EPS);
;             bf16_t* dst = (bf16_t*)(a.ws + (which ? WS_KWN : WS_KSN));
;             dst[(size_t)row * 128 + g * 64 + lane] = (bf16_t)f2bf(v[i] * rstd * kg); }
	v_add_f32_e32 v228, v228, v230
	v_add_f32_e32 v229, v229, v231
	v_add_f32_e32 v244, v244, v246
	v_add_f32_e32 v245, v245, v247
	v_add_f32_dpp v228, v228, v228 row_ror:8 row_mask:0xf bank_mask:0xf
	v_add_f32_dpp v229, v229, v229 row_ror:8 row_mask:0xf bank_mask:0xf
	v_add_f32_dpp v244, v244, v244 row_ror:8 row_mask:0xf bank_mask:0xf
	v_add_f32_dpp v245, v245, v245 row_ror:8 row_mask:0xf bank_mask:0xf
	v_fma_f32 v228, v228, s22, v195
	v_fma_f32 v229, v229, s22, v195
	v_fma_f32 v244, v244, s22, v195
	v_fma_f32 v245, v245, s22, v195
	v_mul_f32_e32 v232, 0x4b800000, v228
	v_mul_f32_e32 v233, 0x4b800000, v229
	v_cmp_gt_f32_e64 s[4:5], s48, v228
	v_cmp_gt_f32_e32 vcc, s48, v229
	s_nop 1
	v_cndmask_b32_e64 v228, v228, v232, s[4:5]
	v_cndmask_b32_e32 v229, v229, v233, vcc
	v_rsq_f32_e32 v228, v228
	v_rsq_f32_e32 v229, v229
	s_nop 0
	v_mul_f32_e32 v232, 0x45800000, v228
	v_mul_f32_e32 v233, 0x45800000, v229
	v_cndmask_b32_e64 v228, v228, v232, s[4:5]
	v_cndmask_b32_e32 v229, v229, v233, vcc
	v_mul_f32_e32 v220, v228, v220
	v_mul_f32_e32 v221, v229, v221
	v_mul_f32_e32 v222, v228, v222
	v_mul_f32_e32 v223, v229, v223
	v_mul_f32_e32 v220, v184, v220
	v_mul_f32_e32 v221, v185, v221
	v_mul_f32_e32 v222, v186, v222
	v_mul_f32_e32 v223, v187, v223
	v_bfe_u32 v224, v220, 16, 1
	v_bfe_u32 v225, v221, 16, 1
	v_bfe_u32 v226, v222, 16, 1
	v_bfe_u32 v227, v223, 16, 1
	v_add3_u32 v220, v220, v224, s49
	v_add3_u32 v221, v221, v225, s49
	v_add3_u32 v222, v222, v226, s49
	v_add3_u32 v223, v223, v227, s49
	v_perm_b32 v234, v221, v220, v194
	v_perm_b32 v235, v223, v222, v194
	global_store_dwordx2 v[200:201], v[234:235], off
	v_mul_f32_e32 v248, 0x4b800000, v244
	v_mul_f32_e32 v249, 0x4b800000, v245
	v_cmp_gt_f32_e64 s[4:5], s48, v244
	v_cmp_gt_f32_e32 vcc, s48, v245
	s_nop 1
	v_cndmask_b32_e64 v244, v244, v248, s[4:5]
	v_cndmask_b32_e32 v245, v245, v249, vcc
	v_rsq_f32_e32 v244, v244
	v_rsq_f32_e32 v245, v245
	s_nop 0
	v_mul_f32_e32 v248, 0x45800000, v244
	v_mul_f32_e32 v249, 0x45800000, v245
	v_cndmask_b32_e64 v244, v244, v248, s[4:5]
	v_cndmask_b32_e32 v245, v245, v249, vcc
	v_mul_f32_e32 v236, v244, v236
	v_mul_f32_e32 v237, v245, v237
	v_mul_f32_e32 v238, v244, v238
	v_mul_f32_e32 v239, v245, v239
	v_mul_f32_e32 v236, v184, v236
	v_mul_f32_e32 v237, v185, v237
	v_mul_f32_e32 v238, v186, v238
	v_mul_f32_e32 v239, v187, v239
	v_bfe_u32 v240, v236, 16, 1
	v_bfe_u32 v241, v237, 16, 1
	v_bfe_u32 v242, v238, 16, 1
	v_bfe_u32 v243, v239, 16, 1
	v_add3_u32 v236, v236, v240, s49
	v_add3_u32 v237, v237, v241, s49
	v_add3_u32 v238, v238, v242, s49
	v_add3_u32 v239, v239, v243, s49
	v_perm_b32 v250, v237, v236, v194
	v_perm_b32 v251, v239, v238, v194
	global_store_dwordx2 v[200:201], v[250:251], off offset:256
	s_waitcnt vmcnt(6)
	v_lshlrev_b32_e32 v220, 16, v20
	v_and_b32_e32 v221, 0xffff0000, v20
	v_lshlrev_b32_e32 v222, 16, v21
	v_and_b32_e32 v223, 0xffff0000, v21
	v_lshlrev_b32_e32 v236, 16, v22
	v_and_b32_e32 v237, 0xffff0000, v22
	v_lshlrev_b32_e32 v238, 16, v23
	v_and_b32_e32 v239, 0xffff0000, v23
	v_mul_f32_e32 v224, v220, v220
	v_mul_f32_e32 v225, v221, v221
	v_mul_f32_e32 v226, v222, v222
	v_mul_f32_e32 v227, v223, v223
	v_mul_f32_e32 v240, v236, v236
	v_mul_f32_e32 v241, v237, v237
	v_mul_f32_e32 v242, v238, v238
	v_mul_f32_e32 v243, v239, v239
	v_fma_f32 v228, v220, v220, v225
	v_fma_f32 v229, v221, v221, v224
	v_fma_f32 v230, v222, v222, v227
	v_fma_f32 v231, v223, v223, v226
	v_fma_f32 v244, v236, v236, v241
	v_fma_f32 v245, v237, v237, v240
	v_fma_f32 v246, v238, v238, v243
	v_fma_f32 v247, v239, v239, v242
	v_add_f32_e32 v228, v228, v230
	v_add_f32_e32 v229, v229, v231
	v_add_f32_e32 v244, v244, v246
	v_add_f32_e32 v245, v245, v247
	v_add_f32_dpp v228, v228, v228 quad_perm:[1,0,3,2] row_mask:0xf bank_mask:0xf
	v_add_f32_dpp v229, v229, v229 quad_perm:[1,0,3,2] row_mask:0xf bank_mask:0xf
	v_add_f32_dpp v244, v244, v244 quad_perm:[1,0,3,2] row_mask:0xf bank_mask:0xf
	v_add_f32_dpp v245, v245, v245 quad_perm:[1,0,3,2] row_mask:0xf bank_mask:0xf
	v_add_f32_dpp v228, v228, v228 quad_perm:[2,3,0,1] row_mask:0xf bank_mask:0xf
	v_add_f32_dpp v229, v229, v229 quad_perm:[2,3,0,1] row_mask:0xf bank_mask:0xf
	v_add_f32_dpp v244, v244, v244 quad_perm:[2,3,0,1] row_mask:0xf bank_mask:0xf
	v_add_f32_dpp v245, v245, v245 quad_perm:[2,3,0,1] row_mask:0xf bank_mask:0xf
	ds_bpermute_b32 v230, v11, v228
	ds_bpermute_b32 v231, v11, v229
	ds_bpermute_b32 v246, v11, v244
	ds_bpermute_b32 v247, v11, v245
	s_waitcnt lgkmcnt(0)
; __device__ __forceinline__ float bf2f(unsigned short u) { return __uint_as_float((unsigned)u << 16); }
; __device__ __forceinline__ unsigned f2bf(float f) { unsigned u = __float_as_uint(f); return (u + 0x7fffu + ((u >> 16) & 1u)) >> 16; }
; __device__ __forceinline__ void knorm_item(const KArgs& a, int l, int item, int wave, int lane) {
;     ...
;     for (int r0 = 0; r0 < 128; r0 += 16) {
;         float v[16];
; #pragma unroll
;         for (int i = 0; i < 16; ++i) { const int task = item * 1024 + wave * 128 + r0 + i, row = task >> 2, which = (task >> 1) & 1, g = task & 1;
;             v[i] = bf2f(Z[(size_t)row * ZW + (which ? ZC_KW : ZC_KS) + g * 64 + lane]); }
; #pragma unroll
;         for (int i = 0; i < 16; ++i) { const int task = item * 1024 + wave * 128 + r0 + i, row = task >> 2, which = (task >> 1) & 1, g = task & 1;
;             const float rstd = rsqrtf(wave_sum(v[i] * v[i]) * (1.f / 64.f) + EPS);
;             bf16_t* dst = (bf16_t*)(a.ws + (which ? WS_KWN : WS_KSN));
;             dst[(size_t)row * 128 + g * 64 + lane] = (bf16_t)f2bf(v[i] * rstd * kg); }
	v_add_f32_e32 v228, v228, v230
	v_add_f32_e32 v229, v229, v231
	v_add_f32_e32 v244, v244, v246
	v_add_f32_e32 v245, v245, v247
	v_add_f32_dpp v228, v228, v228 row_ror:8 row_mask:0xf bank_mask:0xf
	v_add_f32_dpp v229, v229, v229 row_ror:8 row_mask:0xf bank_mask:0xf
	v_add_f32_dpp v244, v244, v244 row_ror:8 row_mask:0xf bank_mask:0xf
	v_add_f32_dpp v245, v245, v245 row_ror:8 row_mask:0xf bank_mask:0xf
	v_fma_f32 v228, v228, s22, v195
	v_fma_f32 v229, v229, s22, v195
	v_fma_f32 v244, v244, s22, v195
	v_fma_f32 v245, v245, s22, v195
	v_mul_f32_e32 v232, 0x4b800000, v228
	v_mul_f32_e32 v233, 0x4b800000, v229
	v_cmp_gt_f32_e64 s[4:5], s48, v228
	v_cmp_gt_f32_e32 vcc, s48, v229
	s_nop 1
	v_cndmask_b32_e64 v228, v228, v232, s[4:5]
	v_cndmask_b32_e32 v229, v229, v233, vcc
	v_rsq_f32_e32 v228, v228
	v_rsq_f32_e32 v229, v229
	s_nop 0
	v_mul_f32_e32 v232, 0x45800000, v228
	v_mul_f32_e32 v233, 0x45800000, v229
	v_cndmask_b32_e64 v228, v228, v232, s[4:5]
	v_cndmask_b32_e32 v229, v229, v233, vcc
	v_mul_f32_e32 v220, v228, v220
	v_mul_f32_e32 v221, v229, v221
	v_mul_f32_e32 v222, v228, v222
	v_mul_f32_e32 v223, v229, v223
	v_mul_f32_e32 v220, v184, v220
	v_mul_f32_e32 v221, v185, v221
	v_mul_f32_e32 v222, v186, v222
	v_mul_f32_e32 v223, v187, v223
	v_bfe_u32 v224, v220, 16, 1
	v_bfe_u32 v225, v221, 16, 1
	v_bfe_u32 v226, v222, 16, 1
	v_bfe_u32 v227, v223, 16, 1
	v_add3_u32 v220, v220, v224, s49
	v_add3_u32 v221, v221, v225, s49
	v_add3_u32 v222, v222, v226, s49
	v_add3_u32 v223, v223, v227, s49
	v_perm_b32 v234, v221, v220, v194
	v_perm_b32 v235, v223, v222, v194
	global_store_dwordx2 v[200:201], v[234:235], off offset:512
	v_mul_f32_e32 v248, 0x4b800000, v244
	v_mul_f32_e32 v249, 0x4b800000, v245
	v_cmp_gt_f32_e64 s[4:5], s48, v244
	v_cmp_gt_f32_e32 vcc, s48, v245
	s_nop 1
	v_cndmask_b32_e64 v244, v244, v248, s[4:5]
	v_cndmask_b32_e32 v245, v245, v249, vcc
	v_rsq_f32_e32 v244, v244
	v_rsq_f32_e32 v245, v245
	s_nop 0
	v_mul_f32_e32 v248, 0x45800000, v244
	v_mul_f32_e32 v249, 0x45800000, v245
	v_cndmask_b32_e64 v244, v244, v248, s[4:5]
	v_cndmask_b32_e32 v245, v245, v249, vcc
	v_mul_f32_e32 v236, v244, v236
	v_mul_f32_e32 v237, v245, v237
	v_mul_f32_e32 v238, v244, v238
	v_mul_f32_e32 v239, v245, v239
	v_mul_f32_e32 v236, v184, v236
	v_mul_f32_e32 v237, v185, v237
	v_mul_f32_e32 v238, v186, v238
	v_mul_f32_e32 v239, v187, v239
	v_bfe_u32 v240, v236, 16, 1
	v_bfe_u32 v241, v237, 16, 1
	v_bfe_u32 v242, v238, 16, 1
	v_bfe_u32 v243, v239, 16, 1
	v_add3_u32 v236, v236, v240, s49
	v_add3_u32 v237, v237, v241, s49
	v_add3_u32 v238, v238, v242, s49
	v_add3_u32 v239, v239, v243, s49
	v_perm_b32 v250, v237, v236, v194
	v_perm_b32 v251, v239, v238, v194
	global_store_dwordx2 v[200:201], v[250:251], off offset:768
	s_cmpk_gt_i32 s57, 64
	s_cbranch_scc1 .Lkn4_skip_237
	s_add_i32 s0, s24, s57
	s_add_i32 s0, s0, 0xfff80030
	s_ashr_i32 s4, s0, 2
	s_ashr_i32 s5, s4, 31
	s_mul_i32 s0, s4, 0x1a00
	s_mul_hi_i32 s1, s4, 0x1a00
	s_add_u32 s0, s92, s0
	s_addc_u32 s1, s93, s1
	v_lshl_add_u64 v[0:1], s[0:1], 0, v[192:193]
	global_load_dwordx2 v[16:17], v[0:1], off offset:1024
	s_add_u32 s0, s0, 0x1a00
	s_addc_u32 s1, s1, 0
	v_lshl_add_u64 v[2:3], s[0:1], 0, v[192:193]
	global_load_dwordx2 v[18:19], v[2:3], off offset:1024
	s_add_u32 s0, s0, 0x1a00
	s_addc_u32 s1, s1, 0
	v_lshl_add_u64 v[0:1], s[0:1], 0, v[192:193]
	global_load_dwordx2 v[20:21], v[0:1], off offset:1024
	s_add_u32 s0, s0, 0x1a00
	s_addc_u32 s1, s1, 0
	v_lshl_add_u64 v[2:3], s[0:1], 0, v[192:193]
	global_load_dwordx2 v[22:23], v[2:3], off offset:1024
.Lkn4_skip_237:
	s_add_i32 s0, s24, s57
	s_add_i32 s0, s0, 0xfff80020
	s_ashr_i32 s4, s0, 2
	s_ashr_i32 s5, s4, 31
	s_lshl_b64 s[30:31], s[4:5], 8
	v_lshl_add_u64 v[200:201], v[190:191], 0, s[30:31]
	s_waitcnt vmcnt(6)
	v_lshlrev_b32_e32 v220, 16, v24
	v_and_b32_e32 v221, 0xffff0000, v24
	v_lshlrev_b32_e32 v222, 16, v25
	v_and_b32_e32 v223, 0xffff0000, v25
	v_lshlrev_b32_e32 v236, 16, v26
	v_and_b32_e32 v237, 0xffff0000, v26
	v_lshlrev_b32_e32 v238, 16, v27
	v_and_b32_e32 v239, 0xffff0000, v27
	v_mul_f32_e32 v224, v220, v220
	v_mul_f32_e32 v225, v221, v221
	v_mul_f32_e32 v226, v222, v222
	v_mul_f32_e32 v227, v223, v223
	v_mul_f32_e32 v240, v236, v236
	v_mul_f32_e32 v241, v237, v237
	v_mul_f32_e32 v242, v238, v238
	v_mul_f32_e32 v243, v239, v239
	v_fma_f32 v228, v220, v220, v225
	v_fma_f32 v229, v221, v221, v224
	v_fma_f32 v230, v222, v222, v227
	v_fma_f32 v231, v223, v223, v226
	v_fma_f32 v244, v236, v236, v241
	v_fma_f32 v245, v237, v237, v240
	v_fma_f32 v246, v238, v238, v243
	v_fma_f32 v247, v239, v239, v242
	v_add_f32_e32 v228, v228, v230
	v_add_f32_e32 v229, v229, v231
	v_add_f32_e32 v244, v244, v246
	v_add_f32_e32 v245, v245, v247
	v_add_f32_dpp v228, v228, v228 quad_perm:[1,0,3,2] row_mask:0xf bank_mask:0xf
	v_add_f32_dpp v229, v229, v229 quad_perm:[1,0,3,2] row_mask:0xf bank_mask:0xf
	v_add_f32_dpp v244, v244, v244 quad_perm:[1,0,3,2] row_mask:0xf bank_mask:0xf
	v_add_f32_dpp v245, v245, v245 quad_perm:[1,0,3,2] row_mask:0xf bank_mask:0xf
	v_add_f32_dpp v228, v228, v228 quad_perm:[2,3,0,1] row_mask:0xf bank_mask:0xf
	v_add_f32_dpp v229, v229, v229 quad_perm:[2,3,0,1] row_mask:0xf bank_mask:0xf
	v_add_f32_dpp v244, v244, v244 quad_perm:[2,3,0,1] row_mask:0xf bank_mask:0xf
	v_add_f32_dpp v245, v245, v245 quad_perm:[2,3,0,1] row_mask:0xf bank_mask:0xf
	ds_bpermute_b32 v230, v11, v228
	ds_bpermute_b32 v231, v11, v229
	ds_bpermute_b32 v246, v11, v244
	ds_bpermute_b32 v247, v11, v245
	s_waitcnt lgkmcnt(0)
; __device__ __forceinline__ float bf2f(unsigned short u) { return __uint_as_float((unsigned)u << 16); }
; __device__ __forceinline__ unsigned f2bf(float f) { unsigned u = __float_as_uint(f); return (u + 0x7fffu + ((u >> 16) & 1u)) >> 16; }
; __device__ __forceinline__ void knorm_item(const KArgs& a, int l, int item, int wave, int lane) {
;     ...
;     for (int r0 = 0; r0 < 128; r0 += 16) {
;         float v[16];
; #pragma unroll
;         for (int i = 0; i < 16; ++i) { const int task = item * 1024 + wave * 128 + r0 + i, row = task >> 2, which = (task >> 1) & 1, g = task & 1;
;             v[i] = bf2f(Z[(size_t)row * ZW + (which ? ZC_KW : ZC_KS) + g * 64 + lane]); }
; #pragma unroll
;         for (int i = 0; i < 16; ++i) { const int task = item * 1024 + wave * 128 + r0 + i, row = task >> 2, which = (task >> 1) & 1, g = task & 1;
;             const float rstd = rsqrtf(wave_sum(v[i] * v[i]) * (1.f / 64.f) + EPS);
;             bf16_t* dst = (bf16_t*)(a.ws + (which ? WS_KWN : WS_KSN));
;             dst[(size_t)row * 128 + g * 64 + lane] = (bf16_t)f2bf(v[i] * rstd * kg); }
	v_add_f32_e32 v228, v228, v230
	v_add_f32_e32 v229, v229, v231
	v_add_f32_e32 v244, v244, v246
	v_add_f32_e32 v245, v245, v247
	v_add_f32_dpp v228, v228, v228 row_ror:8 row_mask:0xf bank_mask:0xf
	v_add_f32_dpp v229, v229, v229 row_ror:8 row_mask:0xf bank_mask:0xf
	v_add_f32_dpp v244, v244, v244 row_ror:8 row_mask:0xf bank_mask:0xf
	v_add_f32_dpp v245, v245, v245 row_ror:8 row_mask:0xf bank_mask:0xf
	v_fma_f32 v228, v228, s22, v195
	v_fma_f32 v229, v229, s22, v195
	v_fma_f32 v244, v244, s22, v195
	v_fma_f32 v245, v245, s22, v195
	v_mul_f32_e32 v232, 0x4b800000, v228
	v_mul_f32_e32 v233, 0x4b800000, v229
	v_cmp_gt_f32_e64 s[4:5], s48, v228
	v_cmp_gt_f32_e32 vcc, s48, v229
	s_nop 1
	v_cndmask_b32_e64 v228, v228, v232, s[4:5]
	v_cndmask_b32_e32 v229, v229, v233, vcc
	v_rsq_f32_e32 v228, v228
	v_rsq_f32_e32 v229, v229
	s_nop 0
	v_mul_f32_e32 v232, 0x45800000, v228
	v_mul_f32_e32 v233, 0x45800000, v229
	v_cndmask_b32_e64 v228, v228, v232, s[4:5]
	v_cndmask_b32_e32 v229, v229, v233, vcc
	v_mul_f32_e32 v220, v228, v220
	v_mul_f32_e32 v221, v229, v221
	v_mul_f32_e32 v222, v228, v222
	v_mul_f32_e32 v223, v229, v223
	v_mul_f32_e32 v220, v184, v220
	v_mul_f32_e32 v221, v185, v221
	v_mul_f32_e32 v222, v186, v222
	v_mul_f32_e32 v223, v187, v223
	v_bfe_u32 v224, v220, 16, 1
	v_bfe_u32 v225, v221, 16, 1
	v_bfe_u32 v226, v222, 16, 1
	v_bfe_u32 v227, v223, 16, 1
	v_add3_u32 v220, v220, v224, s49
	v_add3_u32 v221, v221, v225, s49
	v_add3_u32 v222, v222, v226, s49
	v_add3_u32 v223, v223, v227, s49
	v_perm_b32 v234, v221, v220, v194
	v_perm_b32 v235, v223, v222, v194
	global_store_dwordx2 v[200:201], v[234:235], off
	v_mul_f32_e32 v248, 0x4b800000, v244
	v_mul_f32_e32 v249, 0x4b800000, v245
	v_cmp_gt_f32_e64 s[4:5], s48, v244
	v_cmp_gt_f32_e32 vcc, s48, v245
	s_nop 1
	v_cndmask_b32_e64 v244, v244, v248, s[4:5]
	v_cndmask_b32_e32 v245, v245, v249, vcc
	v_rsq_f32_e32 v244, v244
	v_rsq_f32_e32 v245, v245
	s_nop 0
	v_mul_f32_e32 v248, 0x45800000, v244
	v_mul_f32_e32 v249, 0x45800000, v245
	v_cndmask_b32_e64 v244, v244, v248, s[4:5]
	v_cndmask_b32_e32 v245, v245, v249, vcc
	v_mul_f32_e32 v236, v244, v236
	v_mul_f32_e32 v237, v245, v237
	v_mul_f32_e32 v238, v244, v238
	v_mul_f32_e32 v239, v245, v239
	v_mul_f32_e32 v236, v184, v236
	v_mul_f32_e32 v237, v185, v237
	v_mul_f32_e32 v238, v186, v238
	v_mul_f32_e32 v239, v187, v239
	v_bfe_u32 v240, v236, 16, 1
	v_bfe_u32 v241, v237, 16, 1
	v_bfe_u32 v242, v238, 16, 1
	v_bfe_u32 v243, v239, 16, 1
	v_add3_u32 v236, v236, v240, s49
	v_add3_u32 v237, v237, v241, s49
	v_add3_u32 v238, v238, v242, s49
	v_add3_u32 v239, v239, v243, s49
	v_perm_b32 v250, v237, v236, v194
	v_perm_b32 v251, v239, v238, v194
	global_store_dwordx2 v[200:201], v[250:251], off offset:256
	s_waitcnt vmcnt(6)
	v_lshlrev_b32_e32 v220, 16, v196
	v_and_b32_e32 v221, 0xffff0000, v196
	v_lshlrev_b32_e32 v222, 16, v197
	v_and_b32_e32 v223, 0xffff0000, v197
	v_lshlrev_b32_e32 v236, 16, v198
	v_and_b32_e32 v237, 0xffff0000, v198
	v_lshlrev_b32_e32 v238, 16, v199
	v_and_b32_e32 v239, 0xffff0000, v199
	v_mul_f32_e32 v224, v220, v220
	v_mul_f32_e32 v225, v221, v221
	v_mul_f32_e32 v226, v222, v222
	v_mul_f32_e32 v227, v223, v223
	v_mul_f32_e32 v240, v236, v236
	v_mul_f32_e32 v241, v237, v237
	v_mul_f32_e32 v242, v238, v238
	v_mul_f32_e32 v243, v239, v239
	v_fma_f32 v228, v220, v220, v225
	v_fma_f32 v229, v221, v221, v224
	v_fma_f32 v230, v222, v222, v227
	v_fma_f32 v231, v223, v223, v226
	v_fma_f32 v244, v236, v236, v241
	v_fma_f32 v245, v237, v237, v240
	v_fma_f32 v246, v238, v238, v243
	v_fma_f32 v247, v239, v239, v242
	v_add_f32_e32 v228, v228, v230
	v_add_f32_e32 v229, v229, v231
	v_add_f32_e32 v244, v244, v246
	v_add_f32_e32 v245, v245, v247
	v_add_f32_dpp v228, v228, v228 quad_perm:[1,0,3,2] row_mask:0xf bank_mask:0xf
	v_add_f32_dpp v229, v229, v229 quad_perm:[1,0,3,2] row_mask:0xf bank_mask:0xf
	v_add_f32_dpp v244, v244, v244 quad_perm:[1,0,3,2] row_mask:0xf bank_mask:0xf
	v_add_f32_dpp v245, v245, v245 quad_perm:[1,0,3,2] row_mask:0xf bank_mask:0xf
	v_add_f32_dpp v228, v228, v228 quad_perm:[2,3,0,1] row_mask:0xf bank_mask:0xf
	v_add_f32_dpp v229, v229, v229 quad_perm:[2,3,0,1] row_mask:0xf bank_mask:0xf
	v_add_f32_dpp v244, v244, v244 quad_perm:[2,3,0,1] row_mask:0xf bank_mask:0xf
	v_add_f32_dpp v245, v245, v245 quad_perm:[2,3,0,1] row_mask:0xf bank_mask:0xf
	ds_bpermute_b32 v230, v11, v228
	ds_bpermute_b32 v231, v11, v229
	ds_bpermute_b32 v246, v11, v244
	ds_bpermute_b32 v247, v11, v245
	s_waitcnt lgkmcnt(0)
; __device__ __forceinline__ float bf2f(unsigned short u) { return __uint_as_float((unsigned)u << 16); }
; __device__ __forceinline__ unsigned f2bf(float f) { unsigned u = __float_as_uint(f); return (u + 0x7fffu + ((u >> 16) & 1u)) >> 16; }
; __device__ __forceinline__ void knorm_item(const KArgs& a, int l, int item, int wave, int lane) {
;     ...
;     for (int r0 = 0; r0 < 128; r0 += 16) {
;         float v[16];
; #pragma unroll
;         for (int i = 0; i < 16; ++i) { const int task = item * 1024 + wave * 128 + r0 + i, row = task >> 2, which = (task >> 1) & 1, g = task & 1;
;             v[i] = bf2f(Z[(size_t)row * ZW + (which ? ZC_KW : ZC_KS) + g * 64 + lane]); }
; #pragma unroll
;         for (int i = 0; i < 16; ++i) { const int task = item * 1024 + wave * 128 + r0 + i, row = task >> 2, which = (task >> 1) & 1, g = task & 1;
;             const float rstd = rsqrtf(wave_sum(v[i] * v[i]) * (1.f / 64.f) + EPS);
;             bf16_t* dst = (bf16_t*)(a.ws + (which ? WS_KWN : WS_KSN));
;             dst[(size_t)row * 128 + g * 64 + lane] = (bf16_t)f2bf(v[i] * rstd * kg); }
	v_add_f32_e32 v228, v228, v230
	v_add_f32_e32 v229, v229, v231
	v_add_f32_e32 v244, v244, v246
	v_add_f32_e32 v245, v245, v247
	v_add_f32_dpp v228, v228, v228 row_ror:8 row_mask:0xf bank_mask:0xf
	v_add_f32_dpp v229, v229, v229 row_ror:8 row_mask:0xf bank_mask:0xf
	v_add_f32_dpp v244, v244, v244 row_ror:8 row_mask:0xf bank_mask:0xf
	v_add_f32_dpp v245, v245, v245 row_ror:8 row_mask:0xf bank_mask:0xf
	v_fma_f32 v228, v228, s22, v195
	v_fma_f32 v229, v229, s22, v195
	v_fma_f32 v244, v244, s22, v195
	v_fma_f32 v245, v245, s22, v195
	v_mul_f32_e32 v232, 0x4b800000, v228
	v_mul_f32_e32 v233, 0x4b800000, v229
	v_cmp_gt_f32_e64 s[4:5], s48, v228
	v_cmp_gt_f32_e32 vcc, s48, v229
	s_nop 1
	v_cndmask_b32_e64 v228, v228, v232, s[4:5]
	v_cndmask_b32_e32 v229, v229, v233, vcc
	v_rsq_f32_e32 v228, v228
	v_rsq_f32_e32 v229, v229
	s_nop 0
	v_mul_f32_e32 v232, 0x45800000, v228
	v_mul_f32_e32 v233, 0x45800000, v229
	v_cndmask_b32_e64 v228, v228, v232, s[4:5]
	v_cndmask_b32_e32 v229, v229, v233, vcc
	v_mul_f32_e32 v220, v228, v220
	v_mul_f32_e32 v221, v229, v221
	v_mul_f32_e32 v222, v228, v222
	v_mul_f32_e32 v223, v229, v223
	v_mul_f32_e32 v220, v184, v220
	v_mul_f32_e32 v221, v185, v221
	v_mul_f32_e32 v222, v186, v222
	v_mul_f32_e32 v223, v187, v223
	v_bfe_u32 v224, v220, 16, 1
	v_bfe_u32 v225, v221, 16, 1
	v_bfe_u32 v226, v222, 16, 1
	v_bfe_u32 v227, v223, 16, 1
	v_add3_u32 v220, v220, v224, s49
	v_add3_u32 v221, v221, v225, s49
	v_add3_u32 v222, v222, v226, s49
	v_add3_u32 v223, v223, v227, s49
	v_perm_b32 v234, v221, v220, v194
	v_perm_b32 v235, v223, v222, v194
	global_store_dwordx2 v[200:201], v[234:235], off offset:512
	v_mul_f32_e32 v248, 0x4b800000, v244
	v_mul_f32_e32 v249, 0x4b800000, v245
	v_cmp_gt_f32_e64 s[4:5], s48, v244
	v_cmp_gt_f32_e32 vcc, s48, v245
	s_nop 1
	v_cndmask_b32_e64 v244, v244, v248, s[4:5]
	v_cndmask_b32_e32 v245, v245, v249, vcc
	v_rsq_f32_e32 v244, v244
	v_rsq_f32_e32 v245, v245
	s_nop 0
	v_mul_f32_e32 v248, 0x45800000, v244
	v_mul_f32_e32 v249, 0x45800000, v245
	v_cndmask_b32_e64 v244, v244, v248, s[4:5]
	v_cndmask_b32_e32 v245, v245, v249, vcc
	v_mul_f32_e32 v236, v244, v236
	v_mul_f32_e32 v237, v245, v237
	v_mul_f32_e32 v238, v244, v238
	v_mul_f32_e32 v239, v245, v239
	v_mul_f32_e32 v236, v184, v236
	v_mul_f32_e32 v237, v185, v237
	v_mul_f32_e32 v238, v186, v238
	v_mul_f32_e32 v239, v187, v239
	v_bfe_u32 v240, v236, 16, 1
	v_bfe_u32 v241, v237, 16, 1
	v_bfe_u32 v242, v238, 16, 1
	v_bfe_u32 v243, v239, 16, 1
	v_add3_u32 v236, v236, v240, s49
	v_add3_u32 v237, v237, v241, s49
	v_add3_u32 v238, v238, v242, s49
	v_add3_u32 v239, v239, v243, s49
	v_perm_b32 v250, v237, v236, v194
	v_perm_b32 v251, v239, v238, v194
	global_store_dwordx2 v[200:201], v[250:251], off offset:768
	s_add_i32 s57, s57, 32
	s_cmpk_gt_u32 s57, 0x6f
	s_cbranch_scc0 .LBB0_237
	s_mov_b64 s[0:1], 0

; __device__ __forceinline__ float bf2f(unsigned short u) { return __uint_as_float((unsigned)u << 16); }
; __device__ __forceinline__ unsigned f2bf(float f) { unsigned u = __float_as_uint(f); return (u + 0x7fffu + ((u >> 16) & 1u)) >> 16; }
; __device__ __forceinline__ void knorm_item(const KArgs& a, int l, int item, int wave, int lane) {
;     const bf16_t* Z = (const bf16_t*)(a.ws + WS_Z);
;     const float kg = a.in[I_KN][l * 64 + lane];
;     for (int r0 = 0; r0 < 128; r0 += 16) {
;         float v[16];
; #pragma unroll
;         for (int i = 0; i < 16; ++i) { const int task = item * 1024 + wave * 128 + r0 + i, row = task >> 2, which = (task >> 1) & 1, g = task & 1;
;             v[i] = bf2f(Z[(size_t)row * ZW + (which ? ZC_KW : ZC_KS) + g * 64 + lane]); }
; #pragma unroll
;         for (int i = 0; i < 16; ++i) { const int task = item * 1024 + wave * 128 + r0 + i, row = task >> 2, which = (task >> 1) & 1, g = task & 1;
;             const float rstd = rsqrtf(wave_sum(v[i] * v[i]) * (1.f / 64.f) + EPS);
;             bf16_t* dst = (bf16_t*)(a.ws + (which ? WS_KWN : WS_KSN));
;             dst[(size_t)row * 128 + g * 64 + lane] = (bf16_t)f2bf(v[i] * rstd * kg); }
; __device__ __forceinline__ void phase_mix1(const KArgs& a, int l, LAS unsigned char* lds, int wave, int lane, int ci) {
;     ...
;         __syncthreads();
;         if (threadIdx.x == 0) *slot = (int)atomicAdd(ctr, 1u);
;         __syncthreads();
;         int r = *slot;
;         if (r >= N_R0 + N_CMP + N_CONV + N_KN) break;
;         if (r < N_R0) { ret0_item(a, l, r, lds, wave, lane); continue; } r -= N_R0;
;         if (r < N_CMP) { cmp_mfma_item(a, l, r, lds, wave, lane); continue; } r -= N_CMP;
;         if (r < N_CONV) { conv_item(a, l, r); continue; } r -= N_CONV;
;         knorm_item(a, l, r, wave, lane);
.LBB0_1033:
	s_or_b64 exec, exec, s[0:1]
	s_waitcnt lgkmcnt(0)
	s_barrier
	ds_read_b32 v0, v120
	s_movk_i32 s0, 0x2ff
	s_waitcnt lgkmcnt(0)
	v_cmp_lt_i32_e32 vcc, s0, v0
	v_readfirstlane_b32 s33, v0
	s_mov_b64 s[0:1], -1
	s_cbranch_vccnz .LBB0_1028
	s_cmpk_gt_i32 s33, 0x7f
	s_cbranch_scc0 .LBB0_1063
	s_cmpk_gt_u32 s33, 0xff
	s_cbranch_scc0 .LBB0_1044
	s_cmpk_gt_u32 s33, 0x1ff
	s_cbranch_scc0 .LBB0_1040
	global_load_dword v8, v[66:67], off offset:256
	v_cmp_lt_i32_e32 vcc, v124, v123
	s_lshl_b32 s0, s33, 10
	s_add_i32 s30, s40, s0
	v_cndmask_b32_e32 v0, v122, v124, vcc
	v_cmp_lt_i32_e32 vcc, v125, v123
	v_lshlrev_b32_e32 v9, 2, v0
	s_mov_b32 s63, -16
	v_cndmask_b32_e32 v0, v122, v125, vcc
	v_cmp_lt_i32_e32 vcc, v126, v123
	v_lshlrev_b32_e32 v10, 2, v0
	s_nop 0
	v_cndmask_b32_e32 v0, v122, v126, vcc
	v_cmp_lt_i32_e32 vcc, v127, v123
	v_lshlrev_b32_e32 v11, 2, v0
	s_nop 0
	v_cndmask_b32_e32 v0, v122, v127, vcc
	v_cmp_lt_i32_e32 vcc, v128, v123
	v_lshlrev_b32_e32 v12, 2, v0
	s_nop 0
	v_cndmask_b32_e32 v0, v122, v128, vcc
	v_cmp_lt_i32_e32 vcc, v129, v123
	v_lshlrev_b32_e32 v13, 2, v0
	s_nop 0
	v_cndmask_b32_e32 v0, v122, v129, vcc
	v_lshlrev_b32_e32 v14, 2, v0
	v_mbcnt_lo_u32_b32 v186, -1, 0
	v_mbcnt_hi_u32_b32 v186, -1, v186
	v_and_b32_e32 v188, 15, v186
	v_lshlrev_b32_e32 v188, 4, v188
	v_lshlrev_b32_e32 v187, 2, v186
	v_sub_u32_e32 v188, v188, v187
	v_ashrrev_i32_e32 v189, 31, v188
	v_lshl_add_u64 v[188:189], v[66:67], 0, v[188:189]
	global_load_dwordx4 v[184:187], v[188:189], off offset:256
	v_mbcnt_lo_u32_b32 v202, -1, 0
	v_mbcnt_hi_u32_b32 v202, -1, v202
	v_and_b32_e32 v188, 31, v202
	v_lshlrev_b32_e32 v188, 3, v188
	v_lshlrev_b32_e32 v189, 1, v202
	v_sub_u32_e32 v188, v188, v189
	v_ashrrev_i32_e32 v189, 31, v188
	v_lshl_add_u64 v[190:191], v[68:69], 0, v[188:189]
	v_lshl_add_u64 v[192:193], v[70:71], 0, v[188:189]
	v_cmp_lt_u32_e32 vcc, 31, v202
	v_lshrrev_b32_e32 v203, 5, v202
	v_lshlrev_b32_e32 v203, 9, v203
	v_cndmask_b32_e32 v190, v190, v192, vcc
	v_cndmask_b32_e32 v191, v191, v193, vcc
	v_add_u32_e32 v188, v188, v203
	v_mov_b32_e32 v189, 0
	v_lshl_add_u64 v[192:193], v[64:65], 0, v[188:189]
	v_mov_b32_e32 v188, s53
	v_lshl_add_u64 v[192:193], v[192:193], 0, v[188:189]
	v_mov_b32_e32 v194, 0x7060302
	v_mov_b32_e32 v195, s26
	s_add_i32 s0, s30, s63
	s_add_i32 s0, s0, 0xfff80010
	s_ashr_i32 s4, s0, 2
	s_ashr_i32 s5, s4, 31
	s_mul_i32 s0, s4, 0x1a00
	s_mul_hi_i32 s1, s4, 0x1a00
	s_add_u32 s0, s92, s0
	s_addc_u32 s1, s93, s1
	v_lshl_add_u64 v[0:1], s[0:1], 0, v[192:193]
	global_load_dwordx2 v[16:17], v[0:1], off offset:1024
	s_add_u32 s0, s0, 0x1a00
	s_addc_u32 s1, s1, 0
	v_lshl_add_u64 v[2:3], s[0:1], 0, v[192:193]
	global_load_dwordx2 v[18:19], v[2:3], off offset:1024
	s_add_u32 s0, s0, 0x1a00
	s_addc_u32 s1, s1, 0
	v_lshl_add_u64 v[0:1], s[0:1], 0, v[192:193]
	global_load_dwordx2 v[20:21], v[0:1], off offset:1024
	s_add_u32 s0, s0, 0x1a00
	s_addc_u32 s1, s1, 0
	v_lshl_add_u64 v[2:3], s[0:1], 0, v[192:193]
	global_load_dwordx2 v[22:23], v[2:3], off offset:1024
.LBB0_1038:
	s_add_i32 s0, s30, s63
	s_add_i32 s0, s0, 0xfff80020
	s_ashr_i32 s4, s0, 2
	s_ashr_i32 s5, s4, 31
	s_mul_i32 s0, s4, 0x1a00
	s_mul_hi_i32 s1, s4, 0x1a00
	s_add_u32 s0, s92, s0
	s_addc_u32 s1, s93, s1
	v_lshl_add_u64 v[0:1], s[0:1], 0, v[192:193]
	global_load_dwordx2 v[24:25], v[0:1], off offset:1024
	s_add_u32 s0, s0, 0x1a00
	s_addc_u32 s1, s1, 0
	v_lshl_add_u64 v[2:3], s[0:1], 0, v[192:193]
	global_load_dwordx2 v[26:27], v[2:3], off offset:1024
	s_add_u32 s0, s0, 0x1a00
	s_addc_u32 s1, s1, 0
	v_lshl_add_u64 v[0:1], s[0:1], 0, v[192:193]
	global_load_dwordx2 v[196:197], v[0:1], off offset:1024
	s_add_u32 s0, s0, 0x1a00
	s_addc_u32 s1, s1, 0
	v_lshl_add_u64 v[2:3], s[0:1], 0, v[192:193]
	global_load_dwordx2 v[198:199], v[2:3], off offset:1024
	s_add_i32 s0, s30, s63
	s_add_i32 s0, s0, 0xfff80010
	s_ashr_i32 s4, s0, 2
	s_ashr_i32 s5, s4, 31
	s_lshl_b64 s[38:39], s[4:5], 8
	v_lshl_add_u64 v[200:201], v[190:191], 0, s[38:39]
	s_waitcnt vmcnt(6)
	v_lshlrev_b32_e32 v220, 16, v16
	v_and_b32_e32 v221, 0xffff0000, v16
	v_lshlrev_b32_e32 v222, 16, v17
	v_and_b32_e32 v223, 0xffff0000, v17
	v_lshlrev_b32_e32 v236, 16, v18
	v_and_b32_e32 v237, 0xffff0000, v18
	v_lshlrev_b32_e32 v238, 16, v19
	v_and_b32_e32 v239, 0xffff0000, v19
	v_mul_f32_e32 v224, v220, v220
	v_mul_f32_e32 v225, v221, v221
	v_mul_f32_e32 v226, v222, v222
	v_mul_f32_e32 v227, v223, v223
	v_mul_f32_e32 v240, v236, v236
	v_mul_f32_e32 v241, v237, v237
	v_mul_f32_e32 v242, v238, v238
	v_mul_f32_e32 v243, v239, v239
	v_fma_f32 v228, v220, v220, v225
	v_fma_f32 v229, v221, v221, v224
	v_fma_f32 v230, v222, v222, v227
	v_fma_f32 v231, v223, v223, v226
	v_fma_f32 v244, v236, v236, v241
	v_fma_f32 v245, v237, v237, v240
	v_fma_f32 v246, v238, v238, v243
	v_fma_f32 v247, v239, v239, v242
	v_add_f32_e32 v228, v228, v230
	v_add_f32_e32 v229, v229, v231
	v_add_f32_e32 v244, v244, v246
	v_add_f32_e32 v245, v245, v247
	v_add_f32_dpp v228, v228, v228 quad_perm:[1,0,3,2] row_mask:0xf bank_mask:0xf
	v_add_f32_dpp v229, v229, v229 quad_perm:[1,0,3,2] row_mask:0xf bank_mask:0xf
	v_add_f32_dpp v244, v244, v244 quad_perm:[1,0,3,2] row_mask:0xf bank_mask:0xf
	v_add_f32_dpp v245, v245, v245 quad_perm:[1,0,3,2] row_mask:0xf bank_mask:0xf
	v_add_f32_dpp v228, v228, v228 quad_perm:[2,3,0,1] row_mask:0xf bank_mask:0xf
	v_add_f32_dpp v229, v229, v229 quad_perm:[2,3,0,1] row_mask:0xf bank_mask:0xf
	v_add_f32_dpp v244, v244, v244 quad_perm:[2,3,0,1] row_mask:0xf bank_mask:0xf
	v_add_f32_dpp v245, v245, v245 quad_perm:[2,3,0,1] row_mask:0xf bank_mask:0xf
	ds_bpermute_b32 v230, v11, v228
	ds_bpermute_b32 v231, v11, v229
	ds_bpermute_b32 v246, v11, v244
	ds_bpermute_b32 v247, v11, v245
	s_waitcnt lgkmcnt(0)
; __device__ __forceinline__ float bf2f(unsigned short u) { return __uint_as_float((unsigned)u << 16); }
; __device__ __forceinline__ unsigned f2bf(float f) { unsigned u = __float_as_uint(f); return (u + 0x7fffu + ((u >> 16) & 1u)) >> 16; }
; __device__ __forceinline__ void knorm_item(const KArgs& a, int l, int item, int wave, int lane) {
;     ...
;     for (int r0 = 0; r0 < 128; r0 += 16) {
;         float v[16];
; #pragma unroll
;         for (int i = 0; i < 16; ++i) { const int task = item * 1024 + wave * 128 + r0 + i, row = task >> 2, which = (task >> 1) & 1, g = task & 1;
;             v[i] = bf2f(Z[(size_t)row * ZW + (which ? ZC_KW : ZC_KS) + g * 64 + lane]); }
; #pragma unroll
;         for (int i = 0; i < 16; ++i) { const int task = item * 1024 + wave * 128 + r0 + i, row = task >> 2, which = (task >> 1) & 1, g = task & 1;
;             const float rstd = rsqrtf(wave_sum(v[i] * v[i]) * (1.f / 64.f) + EPS);
;             bf16_t* dst = (bf16_t*)(a.ws + (which ? WS_KWN : WS_KSN));
;             dst[(size_t)row * 128 + g * 64 + lane] = (bf16_t)f2bf(v[i] * rstd * kg); }
	v_add_f32_e32 v228, v228, v230
	v_add_f32_e32 v229, v229, v231
	v_add_f32_e32 v244, v244, v246
	v_add_f32_e32 v245, v245, v247
	v_add_f32_dpp v228, v228, v228 row_ror:8 row_mask:0xf bank_mask:0xf
	v_add_f32_dpp v229, v229, v229 row_ror:8 row_mask:0xf bank_mask:0xf
	v_add_f32_dpp v244, v244, v244 row_ror:8 row_mask:0xf bank_mask:0xf
	v_add_f32_dpp v245, v245, v245 row_ror:8 row_mask:0xf bank_mask:0xf
	v_fma_f32 v228, v228, s28, v195
	v_fma_f32 v229, v229, s28, v195
	v_fma_f32 v244, v244, s28, v195
	v_fma_f32 v245, v245, s28, v195
	v_mul_f32_e32 v232, 0x4b800000, v228
	v_mul_f32_e32 v233, 0x4b800000, v229
	v_cmp_gt_f32_e64 s[4:5], s54, v228
	v_cmp_gt_f32_e32 vcc, s54, v229
	s_nop 1
	v_cndmask_b32_e64 v228, v228, v232, s[4:5]
	v_cndmask_b32_e32 v229, v229, v233, vcc
	v_rsq_f32_e32 v228, v228
	v_rsq_f32_e32 v229, v229
	s_nop 0
	v_mul_f32_e32 v232, 0x45800000, v228
	v_mul_f32_e32 v233, 0x45800000, v229
	v_cndmask_b32_e64 v228, v228, v232, s[4:5]
	v_cndmask_b32_e32 v229, v229, v233, vcc
	v_mul_f32_e32 v220, v228, v220
	v_mul_f32_e32 v221, v229, v221
	v_mul_f32_e32 v222, v228, v222
	v_mul_f32_e32 v223, v229, v223
	v_mul_f32_e32 v220, v184, v220
	v_mul_f32_e32 v221, v185, v221
	v_mul_f32_e32 v222, v186, v222
	v_mul_f32_e32 v223, v187, v223
	v_bfe_u32 v224, v220, 16, 1
	v_bfe_u32 v225, v221, 16, 1
	v_bfe_u32 v226, v222, 16, 1
	v_bfe_u32 v227, v223, 16, 1
	v_add3_u32 v220, v220, v224, s55
	v_add3_u32 v221, v221, v225, s55
	v_add3_u32 v222, v222, v226, s55
	v_add3_u32 v223, v223, v227, s55
	v_perm_b32 v234, v221, v220, v194
	v_perm_b32 v235, v223, v222, v194
	global_store_dwordx2 v[200:201], v[234:235], off
	v_mul_f32_e32 v248, 0x4b800000, v244
	v_mul_f32_e32 v249, 0x4b800000, v245
	v_cmp_gt_f32_e64 s[4:5], s54, v244
	v_cmp_gt_f32_e32 vcc, s54, v245
	s_nop 1
	v_cndmask_b32_e64 v244, v244, v248, s[4:5]
	v_cndmask_b32_e32 v245, v245, v249, vcc
	v_rsq_f32_e32 v244, v244
	v_rsq_f32_e32 v245, v245
	s_nop 0
	v_mul_f32_e32 v248, 0x45800000, v244
	v_mul_f32_e32 v249, 0x45800000, v245
	v_cndmask_b32_e64 v244, v244, v248, s[4:5]
	v_cndmask_b32_e32 v245, v245, v249, vcc
	v_mul_f32_e32 v236, v244, v236
	v_mul_f32_e32 v237, v245, v237
	v_mul_f32_e32 v238, v244, v238
	v_mul_f32_e32 v239, v245, v239
	v_mul_f32_e32 v236, v184, v236
	v_mul_f32_e32 v237, v185, v237
	v_mul_f32_e32 v238, v186, v238
	v_mul_f32_e32 v239, v187, v239
	v_bfe_u32 v240, v236, 16, 1
	v_bfe_u32 v241, v237, 16, 1
	v_bfe_u32 v242, v238, 16, 1
	v_bfe_u32 v243, v239, 16, 1
	v_add3_u32 v236, v236, v240, s55
	v_add3_u32 v237, v237, v241, s55
	v_add3_u32 v238, v238, v242, s55
	v_add3_u32 v239, v239, v243, s55
	v_perm_b32 v250, v237, v236, v194
	v_perm_b32 v251, v239, v238, v194
	global_store_dwordx2 v[200:201], v[250:251], off offset:256
	s_waitcnt vmcnt(6)
	v_lshlrev_b32_e32 v220, 16, v20
	v_and_b32_e32 v221, 0xffff0000, v20
	v_lshlrev_b32_e32 v222, 16, v21
	v_and_b32_e32 v223, 0xffff0000, v21
	v_lshlrev_b32_e32 v236, 16, v22
	v_and_b32_e32 v237, 0xffff0000, v22
	v_lshlrev_b32_e32 v238, 16, v23
	v_and_b32_e32 v239, 0xffff0000, v23
	v_mul_f32_e32 v224, v220, v220
	v_mul_f32_e32 v225, v221, v221
	v_mul_f32_e32 v226, v222, v222
	v_mul_f32_e32 v227, v223, v223
	v_mul_f32_e32 v240, v236, v236
	v_mul_f32_e32 v241, v237, v237
	v_mul_f32_e32 v242, v238, v238
	v_mul_f32_e32 v243, v239, v239
	v_fma_f32 v228, v220, v220, v225
	v_fma_f32 v229, v221, v221, v224
	v_fma_f32 v230, v222, v222, v227
	v_fma_f32 v231, v223, v223, v226
	v_fma_f32 v244, v236, v236, v241
	v_fma_f32 v245, v237, v237, v240
	v_fma_f32 v246, v238, v238, v243
	v_fma_f32 v247, v239, v239, v242
	v_add_f32_e32 v228, v228, v230
	v_add_f32_e32 v229, v229, v231
	v_add_f32_e32 v244, v244, v246
	v_add_f32_e32 v245, v245, v247
	v_add_f32_dpp v228, v228, v228 quad_perm:[1,0,3,2] row_mask:0xf bank_mask:0xf
	v_add_f32_dpp v229, v229, v229 quad_perm:[1,0,3,2] row_mask:0xf bank_mask:0xf
	v_add_f32_dpp v244, v244, v244 quad_perm:[1,0,3,2] row_mask:0xf bank_mask:0xf
	v_add_f32_dpp v245, v245, v245 quad_perm:[1,0,3,2] row_mask:0xf bank_mask:0xf
	v_add_f32_dpp v228, v228, v228 quad_perm:[2,3,0,1] row_mask:0xf bank_mask:0xf
	v_add_f32_dpp v229, v229, v229 quad_perm:[2,3,0,1] row_mask:0xf bank_mask:0xf
	v_add_f32_dpp v244, v244, v244 quad_perm:[2,3,0,1] row_mask:0xf bank_mask:0xf
	v_add_f32_dpp v245, v245, v245 quad_perm:[2,3,0,1] row_mask:0xf bank_mask:0xf
	ds_bpermute_b32 v230, v11, v228
	ds_bpermute_b32 v231, v11, v229
	ds_bpermute_b32 v246, v11, v244
	ds_bpermute_b32 v247, v11, v245
	s_waitcnt lgkmcnt(0)
; __device__ __forceinline__ float bf2f(unsigned short u) { return __uint_as_float((unsigned)u << 16); }
; __device__ __forceinline__ unsigned f2bf(float f) { unsigned u = __float_as_uint(f); return (u + 0x7fffu + ((u >> 16) & 1u)) >> 16; }
; __device__ __forceinline__ void knorm_item(const KArgs& a, int l, int item, int wave, int lane) {
;     ...
;     for (int r0 = 0; r0 < 128; r0 += 16) {
;         float v[16];
; #pragma unroll
;         for (int i = 0; i < 16; ++i) { const int task = item * 1024 + wave * 128 + r0 + i, row = task >> 2, which = (task >> 1) & 1, g = task & 1;
;             v[i] = bf2f(Z[(size_t)row * ZW + (which ? ZC_KW : ZC_KS) + g * 64 + lane]); }
; #pragma unroll
;         for (int i = 0; i < 16; ++i) { const int task = item * 1024 + wave * 128 + r0 + i, row = task >> 2, which = (task >> 1) & 1, g = task & 1;
;             const float rstd = rsqrtf(wave_sum(v[i] * v[i]) * (1.f / 64.f) + EPS);
;             bf16_t* dst = (bf16_t*)(a.ws + (which ? WS_KWN : WS_KSN));
;             dst[(size_t)row * 128 + g * 64 + lane] = (bf16_t)f2bf(v[i] * rstd * kg); }
	v_add_f32_e32 v228, v228, v230
	v_add_f32_e32 v229, v229, v231
	v_add_f32_e32 v244, v244, v246
	v_add_f32_e32 v245, v245, v247
	v_add_f32_dpp v228, v228, v228 row_ror:8 row_mask:0xf bank_mask:0xf
	v_add_f32_dpp v229, v229, v229 row_ror:8 row_mask:0xf bank_mask:0xf
	v_add_f32_dpp v244, v244, v244 row_ror:8 row_mask:0xf bank_mask:0xf
	v_add_f32_dpp v245, v245, v245 row_ror:8 row_mask:0xf bank_mask:0xf
	v_fma_f32 v228, v228, s28, v195
	v_fma_f32 v229, v229, s28, v195
	v_fma_f32 v244, v244, s28, v195
	v_fma_f32 v245, v245, s28, v195
	v_mul_f32_e32 v232, 0x4b800000, v228
	v_mul_f32_e32 v233, 0x4b800000, v229
	v_cmp_gt_f32_e64 s[4:5], s54, v228
	v_cmp_gt_f32_e32 vcc, s54, v229
	s_nop 1
	v_cndmask_b32_e64 v228, v228, v232, s[4:5]
	v_cndmask_b32_e32 v229, v229, v233, vcc
	v_rsq_f32_e32 v228, v228
	v_rsq_f32_e32 v229, v229
	s_nop 0
	v_mul_f32_e32 v232, 0x45800000, v228
	v_mul_f32_e32 v233, 0x45800000, v229
	v_cndmask_b32_e64 v228, v228, v232, s[4:5]
	v_cndmask_b32_e32 v229, v229, v233, vcc
	v_mul_f32_e32 v220, v228, v220
	v_mul_f32_e32 v221, v229, v221
	v_mul_f32_e32 v222, v228, v222
	v_mul_f32_e32 v223, v229, v223
	v_mul_f32_e32 v220, v184, v220
	v_mul_f32_e32 v221, v185, v221
	v_mul_f32_e32 v222, v186, v222
	v_mul_f32_e32 v223, v187, v223
	v_bfe_u32 v224, v220, 16, 1
	v_bfe_u32 v225, v221, 16, 1
	v_bfe_u32 v226, v222, 16, 1
	v_bfe_u32 v227, v223, 16, 1
	v_add3_u32 v220, v220, v224, s55
	v_add3_u32 v221, v221, v225, s55
	v_add3_u32 v222, v222, v226, s55
	v_add3_u32 v223, v223, v227, s55
	v_perm_b32 v234, v221, v220, v194
	v_perm_b32 v235, v223, v222, v194
	global_store_dwordx2 v[200:201], v[234:235], off offset:512
	v_mul_f32_e32 v248, 0x4b800000, v244
	v_mul_f32_e32 v249, 0x4b800000, v245
	v_cmp_gt_f32_e64 s[4:5], s54, v244
	v_cmp_gt_f32_e32 vcc, s54, v245
	s_nop 1
	v_cndmask_b32_e64 v244, v244, v248, s[4:5]
	v_cndmask_b32_e32 v245, v245, v249, vcc
	v_rsq_f32_e32 v244, v244
	v_rsq_f32_e32 v245, v245
	s_nop 0
	v_mul_f32_e32 v248, 0x45800000, v244
	v_mul_f32_e32 v249, 0x45800000, v245
	v_cndmask_b32_e64 v244, v244, v248, s[4:5]
	v_cndmask_b32_e32 v245, v245, v249, vcc
	v_mul_f32_e32 v236, v244, v236
	v_mul_f32_e32 v237, v245, v237
	v_mul_f32_e32 v238, v244, v238
	v_mul_f32_e32 v239, v245, v239
	v_mul_f32_e32 v236, v184, v236
	v_mul_f32_e32 v237, v185, v237
	v_mul_f32_e32 v238, v186, v238
	v_mul_f32_e32 v239, v187, v239
	v_bfe_u32 v240, v236, 16, 1
	v_bfe_u32 v241, v237, 16, 1
	v_bfe_u32 v242, v238, 16, 1
	v_bfe_u32 v243, v239, 16, 1
	v_add3_u32 v236, v236, v240, s55
	v_add3_u32 v237, v237, v241, s55
	v_add3_u32 v238, v238, v242, s55
	v_add3_u32 v239, v239, v243, s55
	v_perm_b32 v250, v237, v236, v194
	v_perm_b32 v251, v239, v238, v194
	global_store_dwordx2 v[200:201], v[250:251], off offset:768
	s_cmpk_gt_i32 s63, 64
	s_cbranch_scc1 .Lkn4_skip_1038
	s_add_i32 s0, s30, s63
	s_add_i32 s0, s0, 0xfff80030
	s_ashr_i32 s4, s0, 2
	s_ashr_i32 s5, s4, 31
	s_mul_i32 s0, s4, 0x1a00
	s_mul_hi_i32 s1, s4, 0x1a00
	s_add_u32 s0, s92, s0
	s_addc_u32 s1, s93, s1
	v_lshl_add_u64 v[0:1], s[0:1], 0, v[192:193]
	global_load_dwordx2 v[16:17], v[0:1], off offset:1024
	s_add_u32 s0, s0, 0x1a00
	s_addc_u32 s1, s1, 0
	v_lshl_add_u64 v[2:3], s[0:1], 0, v[192:193]
	global_load_dwordx2 v[18:19], v[2:3], off offset:1024
	s_add_u32 s0, s0, 0x1a00
	s_addc_u32 s1, s1, 0
	v_lshl_add_u64 v[0:1], s[0:1], 0, v[192:193]
	global_load_dwordx2 v[20:21], v[0:1], off offset:1024
	s_add_u32 s0, s0, 0x1a00
	s_addc_u32 s1, s1, 0
	v_lshl_add_u64 v[2:3], s[0:1], 0, v[192:193]
	global_load_dwordx2 v[22:23], v[2:3], off offset:1024
.Lkn4_skip_1038:
	s_add_i32 s0, s30, s63
	s_add_i32 s0, s0, 0xfff80020
	s_ashr_i32 s4, s0, 2
	s_ashr_i32 s5, s4, 31
	s_lshl_b64 s[38:39], s[4:5], 8
	v_lshl_add_u64 v[200:201], v[190:191], 0, s[38:39]
	s_waitcnt vmcnt(6)
	v_lshlrev_b32_e32 v220, 16, v24
	v_and_b32_e32 v221, 0xffff0000, v24
	v_lshlrev_b32_e32 v222, 16, v25
	v_and_b32_e32 v223, 0xffff0000, v25
	v_lshlrev_b32_e32 v236, 16, v26
	v_and_b32_e32 v237, 0xffff0000, v26
	v_lshlrev_b32_e32 v238, 16, v27
	v_and_b32_e32 v239, 0xffff0000, v27
	v_mul_f32_e32 v224, v220, v220
	v_mul_f32_e32 v225, v221, v221
	v_mul_f32_e32 v226, v222, v222
	v_mul_f32_e32 v227, v223, v223
	v_mul_f32_e32 v240, v236, v236
	v_mul_f32_e32 v241, v237, v237
	v_mul_f32_e32 v242, v238, v238
	v_mul_f32_e32 v243, v239, v239
	v_fma_f32 v228, v220, v220, v225
	v_fma_f32 v229, v221, v221, v224
	v_fma_f32 v230, v222, v222, v227
	v_fma_f32 v231, v223, v223, v226
	v_fma_f32 v244, v236, v236, v241
	v_fma_f32 v245, v237, v237, v240
	v_fma_f32 v246, v238, v238, v243
	v_fma_f32 v247, v239, v239, v242
	v_add_f32_e32 v228, v228, v230
	v_add_f32_e32 v229, v229, v231
	v_add_f32_e32 v244, v244, v246
	v_add_f32_e32 v245, v245, v247
	v_add_f32_dpp v228, v228, v228 quad_perm:[1,0,3,2] row_mask:0xf bank_mask:0xf
	v_add_f32_dpp v229, v229, v229 quad_perm:[1,0,3,2] row_mask:0xf bank_mask:0xf
	v_add_f32_dpp v244, v244, v244 quad_perm:[1,0,3,2] row_mask:0xf bank_mask:0xf
	v_add_f32_dpp v245, v245, v245 quad_perm:[1,0,3,2] row_mask:0xf bank_mask:0xf
	v_add_f32_dpp v228, v228, v228 quad_perm:[2,3,0,1] row_mask:0xf bank_mask:0xf
	v_add_f32_dpp v229, v229, v229 quad_perm:[2,3,0,1] row_mask:0xf bank_mask:0xf
	v_add_f32_dpp v244, v244, v244 quad_perm:[2,3,0,1] row_mask:0xf bank_mask:0xf
	v_add_f32_dpp v245, v245, v245 quad_perm:[2,3,0,1] row_mask:0xf bank_mask:0xf
	ds_bpermute_b32 v230, v11, v228
	ds_bpermute_b32 v231, v11, v229
	ds_bpermute_b32 v246, v11, v244
	ds_bpermute_b32 v247, v11, v245
	s_waitcnt lgkmcnt(0)
; __device__ __forceinline__ float bf2f(unsigned short u) { return __uint_as_float((unsigned)u << 16); }
; __device__ __forceinline__ unsigned f2bf(float f) { unsigned u = __float_as_uint(f); return (u + 0x7fffu + ((u >> 16) & 1u)) >> 16; }
; __device__ __forceinline__ void knorm_item(const KArgs& a, int l, int item, int wave, int lane) {
;     ...
;     for (int r0 = 0; r0 < 128; r0 += 16) {
;         float v[16];
; #pragma unroll
;         for (int i = 0; i < 16; ++i) { const int task = item * 1024 + wave * 128 + r0 + i, row = task >> 2, which = (task >> 1) & 1, g = task & 1;
;             v[i] = bf2f(Z[(size_t)row * ZW + (which ? ZC_KW : ZC_KS) + g * 64 + lane]); }
; #pragma unroll
;         for (int i = 0; i < 16; ++i) { const int task = item * 1024 + wave * 128 + r0 + i, row = task >> 2, which = (task >> 1) & 1, g = task & 1;
;             const float rstd = rsqrtf(wave_sum(v[i] * v[i]) * (1.f / 64.f) + EPS);
;             bf16_t* dst = (bf16_t*)(a.ws + (which ? WS_KWN : WS_KSN));
;             dst[(size_t)row * 128 + g * 64 + lane] = (bf16_t)f2bf(v[i] * rstd * kg); }
	v_add_f32_e32 v228, v228, v230
	v_add_f32_e32 v229, v229, v231
	v_add_f32_e32 v244, v244, v246
	v_add_f32_e32 v245, v245, v247
	v_add_f32_dpp v228, v228, v228 row_ror:8 row_mask:0xf bank_mask:0xf
	v_add_f32_dpp v229, v229, v229 row_ror:8 row_mask:0xf bank_mask:0xf
	v_add_f32_dpp v244, v244, v244 row_ror:8 row_mask:0xf bank_mask:0xf
	v_add_f32_dpp v245, v245, v245 row_ror:8 row_mask:0xf bank_mask:0xf
	v_fma_f32 v228, v228, s28, v195
	v_fma_f32 v229, v229, s28, v195
	v_fma_f32 v244, v244, s28, v195
	v_fma_f32 v245, v245, s28, v195
	v_mul_f32_e32 v232, 0x4b800000, v228
	v_mul_f32_e32 v233, 0x4b800000, v229
	v_cmp_gt_f32_e64 s[4:5], s54, v228
	v_cmp_gt_f32_e32 vcc, s54, v229
	s_nop 1
	v_cndmask_b32_e64 v228, v228, v232, s[4:5]
	v_cndmask_b32_e32 v229, v229, v233, vcc
	v_rsq_f32_e32 v228, v228
	v_rsq_f32_e32 v229, v229
	s_nop 0
	v_mul_f32_e32 v232, 0x45800000, v228
	v_mul_f32_e32 v233, 0x45800000, v229
	v_cndmask_b32_e64 v228, v228, v232, s[4:5]
	v_cndmask_b32_e32 v229, v229, v233, vcc
	v_mul_f32_e32 v220, v228, v220
	v_mul_f32_e32 v221, v229, v221
	v_mul_f32_e32 v222, v228, v222
	v_mul_f32_e32 v223, v229, v223
	v_mul_f32_e32 v220, v184, v220
	v_mul_f32_e32 v221, v185, v221
	v_mul_f32_e32 v222, v186, v222
	v_mul_f32_e32 v223, v187, v223
	v_bfe_u32 v224, v220, 16, 1
	v_bfe_u32 v225, v221, 16, 1
	v_bfe_u32 v226, v222, 16, 1
	v_bfe_u32 v227, v223, 16, 1
	v_add3_u32 v220, v220, v224, s55
	v_add3_u32 v221, v221, v225, s55
	v_add3_u32 v222, v222, v226, s55
	v_add3_u32 v223, v223, v227, s55
	v_perm_b32 v234, v221, v220, v194
	v_perm_b32 v235, v223, v222, v194
	global_store_dwordx2 v[200:201], v[234:235], off
	v_mul_f32_e32 v248, 0x4b800000, v244
	v_mul_f32_e32 v249, 0x4b800000, v245
	v_cmp_gt_f32_e64 s[4:5], s54, v244
	v_cmp_gt_f32_e32 vcc, s54, v245
	s_nop 1
	v_cndmask_b32_e64 v244, v244, v248, s[4:5]
	v_cndmask_b32_e32 v245, v245, v249, vcc
	v_rsq_f32_e32 v244, v244
	v_rsq_f32_e32 v245, v245
	s_nop 0
	v_mul_f32_e32 v248, 0x45800000, v244
	v_mul_f32_e32 v249, 0x45800000, v245
	v_cndmask_b32_e64 v244, v244, v248, s[4:5]
	v_cndmask_b32_e32 v245, v245, v249, vcc
	v_mul_f32_e32 v236, v244, v236
	v_mul_f32_e32 v237, v245, v237
	v_mul_f32_e32 v238, v244, v238
	v_mul_f32_e32 v239, v245, v239
	v_mul_f32_e32 v236, v184, v236
	v_mul_f32_e32 v237, v185, v237
	v_mul_f32_e32 v238, v186, v238
	v_mul_f32_e32 v239, v187, v239
	v_bfe_u32 v240, v236, 16, 1
	v_bfe_u32 v241, v237, 16, 1
	v_bfe_u32 v242, v238, 16, 1
	v_bfe_u32 v243, v239, 16, 1
	v_add3_u32 v236, v236, v240, s55
	v_add3_u32 v237, v237, v241, s55
	v_add3_u32 v238, v238, v242, s55
	v_add3_u32 v239, v239, v243, s55
	v_perm_b32 v250, v237, v236, v194
	v_perm_b32 v251, v239, v238, v194
	global_store_dwordx2 v[200:201], v[250:251], off offset:256
	s_waitcnt vmcnt(6)
	v_lshlrev_b32_e32 v220, 16, v196
	v_and_b32_e32 v221, 0xffff0000, v196
	v_lshlrev_b32_e32 v222, 16, v197
	v_and_b32_e32 v223, 0xffff0000, v197
	v_lshlrev_b32_e32 v236, 16, v198
	v_and_b32_e32 v237, 0xffff0000, v198
	v_lshlrev_b32_e32 v238, 16, v199
	v_and_b32_e32 v239, 0xffff0000, v199
	v_mul_f32_e32 v224, v220, v220
	v_mul_f32_e32 v225, v221, v221
	v_mul_f32_e32 v226, v222, v222
	v_mul_f32_e32 v227, v223, v223
	v_mul_f32_e32 v240, v236, v236
	v_mul_f32_e32 v241, v237, v237
	v_mul_f32_e32 v242, v238, v238
	v_mul_f32_e32 v243, v239, v239
	v_fma_f32 v228, v220, v220, v225
	v_fma_f32 v229, v221, v221, v224
	v_fma_f32 v230, v222, v222, v227
	v_fma_f32 v231, v223, v223, v226
	v_fma_f32 v244, v236, v236, v241
	v_fma_f32 v245, v237, v237, v240
	v_fma_f32 v246, v238, v238, v243
	v_fma_f32 v247, v239, v239, v242
	v_add_f32_e32 v228, v228, v230
	v_add_f32_e32 v229, v229, v231
	v_add_f32_e32 v244, v244, v246
	v_add_f32_e32 v245, v245, v247
	v_add_f32_dpp v228, v228, v228 quad_perm:[1,0,3,2] row_mask:0xf bank_mask:0xf
	v_add_f32_dpp v229, v229, v229 quad_perm:[1,0,3,2] row_mask:0xf bank_mask:0xf
	v_add_f32_dpp v244, v244, v244 quad_perm:[1,0,3,2] row_mask:0xf bank_mask:0xf
	v_add_f32_dpp v245, v245, v245 quad_perm:[1,0,3,2] row_mask:0xf bank_mask:0xf
	v_add_f32_dpp v228, v228, v228 quad_perm:[2,3,0,1] row_mask:0xf bank_mask:0xf
	v_add_f32_dpp v229, v229, v229 quad_perm:[2,3,0,1] row_mask:0xf bank_mask:0xf
	v_add_f32_dpp v244, v244, v244 quad_perm:[2,3,0,1] row_mask:0xf bank_mask:0xf
	v_add_f32_dpp v245, v245, v245 quad_perm:[2,3,0,1] row_mask:0xf bank_mask:0xf
	ds_bpermute_b32 v230, v11, v228
	ds_bpermute_b32 v231, v11, v229
	ds_bpermute_b32 v246, v11, v244
	ds_bpermute_b32 v247, v11, v245
	s_waitcnt lgkmcnt(0)
; __device__ __forceinline__ float bf2f(unsigned short u) { return __uint_as_float((unsigned)u << 16); }
; __device__ __forceinline__ unsigned f2bf(float f) { unsigned u = __float_as_uint(f); return (u + 0x7fffu + ((u >> 16) & 1u)) >> 16; }
; __device__ __forceinline__ void knorm_item(const KArgs& a, int l, int item, int wave, int lane) {
;     ...
;     for (int r0 = 0; r0 < 128; r0 += 16) {
;         float v[16];
; #pragma unroll
;         for (int i = 0; i < 16; ++i) { const int task = item * 1024 + wave * 128 + r0 + i, row = task >> 2, which = (task >> 1) & 1, g = task & 1;
;             v[i] = bf2f(Z[(size_t)row * ZW + (which ? ZC_KW : ZC_KS) + g * 64 + lane]); }
; #pragma unroll
;         for (int i = 0; i < 16; ++i) { const int task = item * 1024 + wave * 128 + r0 + i, row = task >> 2, which = (task >> 1) & 1, g = task & 1;
;             const float rstd = rsqrtf(wave_sum(v[i] * v[i]) * (1.f / 64.f) + EPS);
;             bf16_t* dst = (bf16_t*)(a.ws + (which ? WS_KWN : WS_KSN));
;             dst[(size_t)row * 128 + g * 64 + lane] = (bf16_t)f2bf(v[i] * rstd * kg); }
	v_add_f32_e32 v228, v228, v230
	v_add_f32_e32 v229, v229, v231
	v_add_f32_e32 v244, v244, v246
	v_add_f32_e32 v245, v245, v247
	v_add_f32_dpp v228, v228, v228 row_ror:8 row_mask:0xf bank_mask:0xf
	v_add_f32_dpp v229, v229, v229 row_ror:8 row_mask:0xf bank_mask:0xf
	v_add_f32_dpp v244, v244, v244 row_ror:8 row_mask:0xf bank_mask:0xf
	v_add_f32_dpp v245, v245, v245 row_ror:8 row_mask:0xf bank_mask:0xf
	v_fma_f32 v228, v228, s28, v195
	v_fma_f32 v229, v229, s28, v195
	v_fma_f32 v244, v244, s28, v195
	v_fma_f32 v245, v245, s28, v195
	v_mul_f32_e32 v232, 0x4b800000, v228
	v_mul_f32_e32 v233, 0x4b800000, v229
	v_cmp_gt_f32_e64 s[4:5], s54, v228
	v_cmp_gt_f32_e32 vcc, s54, v229
	s_nop 1
	v_cndmask_b32_e64 v228, v228, v232, s[4:5]
	v_cndmask_b32_e32 v229, v229, v233, vcc
	v_rsq_f32_e32 v228, v228
	v_rsq_f32_e32 v229, v229
	s_nop 0
	v_mul_f32_e32 v232, 0x45800000, v228
	v_mul_f32_e32 v233, 0x45800000, v229
	v_cndmask_b32_e64 v228, v228, v232, s[4:5]
	v_cndmask_b32_e32 v229, v229, v233, vcc
	v_mul_f32_e32 v220, v228, v220
	v_mul_f32_e32 v221, v229, v221
	v_mul_f32_e32 v222, v228, v222
	v_mul_f32_e32 v223, v229, v223
	v_mul_f32_e32 v220, v184, v220
	v_mul_f32_e32 v221, v185, v221
	v_mul_f32_e32 v222, v186, v222
	v_mul_f32_e32 v223, v187, v223
	v_bfe_u32 v224, v220, 16, 1
	v_bfe_u32 v225, v221, 16, 1
	v_bfe_u32 v226, v222, 16, 1
	v_bfe_u32 v227, v223, 16, 1
	v_add3_u32 v220, v220, v224, s55
	v_add3_u32 v221, v221, v225, s55
	v_add3_u32 v222, v222, v226, s55
	v_add3_u32 v223, v223, v227, s55
	v_perm_b32 v234, v221, v220, v194
	v_perm_b32 v235, v223, v222, v194
	global_store_dwordx2 v[200:201], v[234:235], off offset:512
	v_mul_f32_e32 v248, 0x4b800000, v244
	v_mul_f32_e32 v249, 0x4b800000, v245
	v_cmp_gt_f32_e64 s[4:5], s54, v244
	v_cmp_gt_f32_e32 vcc, s54, v245
	s_nop 1
	v_cndmask_b32_e64 v244, v244, v248, s[4:5]
	v_cndmask_b32_e32 v245, v245, v249, vcc
	v_rsq_f32_e32 v244, v244
	v_rsq_f32_e32 v245, v245
	s_nop 0
	v_mul_f32_e32 v248, 0x45800000, v244
	v_mul_f32_e32 v249, 0x45800000, v245
	v_cndmask_b32_e64 v244, v244, v248, s[4:5]
	v_cndmask_b32_e32 v245, v245, v249, vcc
	v_mul_f32_e32 v236, v244, v236
	v_mul_f32_e32 v237, v245, v237
	v_mul_f32_e32 v238, v244, v238
	v_mul_f32_e32 v239, v245, v239
	v_mul_f32_e32 v236, v184, v236
	v_mul_f32_e32 v237, v185, v237
	v_mul_f32_e32 v238, v186, v238
	v_mul_f32_e32 v239, v187, v239
	v_bfe_u32 v240, v236, 16, 1
	v_bfe_u32 v241, v237, 16, 1
	v_bfe_u32 v242, v238, 16, 1
	v_bfe_u32 v243, v239, 16, 1
	v_add3_u32 v236, v236, v240, s55
	v_add3_u32 v237, v237, v241, s55
	v_add3_u32 v238, v238, v242, s55
	v_add3_u32 v239, v239, v243, s55
	v_perm_b32 v250, v237, v236, v194
	v_perm_b32 v251, v239, v238, v194
	global_store_dwordx2 v[200:201], v[250:251], off offset:768
	s_add_i32 s63, s63, 32
	s_cmpk_gt_u32 s63, 0x6f
	s_cbranch_scc0 .LBB0_1038
	s_mov_b64 s[0:1], 0
